# non-temporal hint on the decode attention's single-use cache-row loads
# baseline (speedup 1.0000x reference)
.LBB0_380:
	v_min_i32_e32 v0, v83, v108
	v_sub_u32_e32 v0, 0x80, v0
	v_add_u32_e32 v123, 1, v83
	v_lshl_add_u32 v6, v0, v111, v85
	v_min_i32_e32 v0, v123, v108
	v_sub_u32_e32 v0, 0x80, v0
	v_add_u32_e32 v122, 2, v83
	v_lshl_add_u32 v8, v0, v111, v85
	v_min_i32_e32 v0, v122, v108
	v_sub_u32_e32 v0, 0x80, v0
	v_add_u32_e32 v117, 3, v83
	v_lshl_add_u32 v10, v0, v111, v85
	v_min_i32_e32 v0, v117, v108
	v_ashrrev_i32_e32 v7, 31, v6
	v_sub_u32_e32 v0, 0x80, v0
	v_add_u32_e32 v116, 4, v83
	v_lshlrev_b64 v[6:7], 11, v[6:7]
	v_ashrrev_i32_e32 v9, 31, v8
	v_lshl_add_u32 v12, v0, v111, v85
	v_min_i32_e32 v0, v116, v108
	v_lshl_add_u64 v[6:7], v[92:93], 0, v[6:7]
	v_lshlrev_b64 v[8:9], 11, v[8:9]
	v_sub_u32_e32 v0, 0x80, v0
	v_add_u32_e32 v115, 5, v83
	global_load_dwordx4 v[66:69], v[6:7], off nt
	v_lshl_add_u64 v[8:9], v[92:93], 0, v[8:9]
	v_lshl_add_u32 v14, v0, v111, v85
	v_min_i32_e32 v0, v115, v108
	global_load_dwordx4 v[62:65], v[8:9], off nt
	v_sub_u32_e32 v0, 0x80, v0
	v_add_u32_e32 v114, 6, v83
	v_ashrrev_i32_e32 v11, 31, v10
	v_ashrrev_i32_e32 v13, 31, v12
	v_lshl_add_u32 v16, v0, v111, v85
	v_min_i32_e32 v0, v114, v108
	v_lshlrev_b64 v[10:11], 11, v[10:11]
	v_lshlrev_b64 v[12:13], 11, v[12:13]
	v_sub_u32_e32 v0, 0x80, v0
	v_lshl_add_u64 v[10:11], v[92:93], 0, v[10:11]
	v_lshl_add_u64 v[12:13], v[92:93], 0, v[12:13]
	v_lshl_add_u32 v18, v0, v111, v85
	global_load_dwordx4 v[58:61], v[10:11], off nt
	global_load_dwordx4 v[54:57], v[12:13], off nt
	v_ashrrev_i32_e32 v15, 31, v14
	v_ashrrev_i32_e32 v17, 31, v16
	v_ashrrev_i32_e32 v19, 31, v18
	v_lshlrev_b64 v[14:15], 11, v[14:15]
	v_lshlrev_b64 v[16:17], 11, v[16:17]
	v_lshlrev_b64 v[18:19], 11, v[18:19]
	v_lshl_add_u64 v[14:15], v[92:93], 0, v[14:15]
	v_lshl_add_u64 v[16:17], v[92:93], 0, v[16:17]
	v_lshl_add_u64 v[96:97], v[92:93], 0, v[18:19]
	global_load_dwordx4 v[50:53], v[14:15], off nt
	global_load_dwordx4 v[46:49], v[16:17], off nt
	global_load_dwordx4 v[42:45], v[96:97], off nt
	v_add_u32_e32 v113, 7, v83
	v_min_i32_e32 v0, v113, v108
	v_sub_u32_e32 v0, 0x80, v0
	v_lshl_add_u32 v18, v0, v111, v85
	v_ashrrev_i32_e32 v19, 31, v18
	v_lshlrev_b64 v[18:19], 11, v[18:19]
	v_lshl_add_u64 v[98:99], v[92:93], 0, v[18:19]
	global_load_dwordx4 v[38:41], v[98:99], off nt
	global_load_dwordx4 v[34:37], v[6:7], off offset:1024 nt
	global_load_dwordx4 v[30:33], v[8:9], off offset:1024 nt
	global_load_dwordx4 v[26:29], v[10:11], off offset:1024 nt
	global_load_dwordx4 v[22:25], v[12:13], off offset:1024 nt
	global_load_dwordx4 v[18:21], v[14:15], off offset:1024 nt
	s_nop 0
	global_load_dwordx4 v[14:17], v[16:17], off offset:1024 nt
	s_nop 0
	global_load_dwordx4 v[10:13], v[96:97], off offset:1024 nt
	global_load_dwordx4 v[6:9], v[98:99], off offset:1024 nt
	s_waitcnt vmcnt(15)
	v_pk_mul_f32 v[96:97], v[66:67], v[88:89]
	v_pk_mul_f32 v[98:99], v[68:69], v[90:91]
	v_add_f32_e32 v0, v96, v97
	v_add_f32_e32 v0, v98, v0
	s_waitcnt vmcnt(14)
	v_pk_mul_f32 v[96:97], v[62:63], v[88:89]
	v_pk_mul_f32 v[100:101], v[64:65], v[90:91]
	v_add_f32_e32 v96, v96, v97
	v_add_f32_e32 v0, v99, v0
	v_add_f32_e32 v96, v100, v96
	v_add_f32_e32 v96, v101, v96
	v_add_f32_dpp v0, v0, v0 quad_perm:[1,0,3,2] row_mask:0xf bank_mask:0xf bound_ctrl:1
	s_waitcnt vmcnt(13)
	v_pk_mul_f32 v[102:103], v[58:59], v[88:89]
	s_waitcnt vmcnt(12)
	v_pk_mul_f32 v[106:107], v[54:55], v[88:89]
	v_add_f32_dpp v0, v0, v0 quad_perm:[2,3,0,1] row_mask:0xf bank_mask:0xf bound_ctrl:1
	v_add_f32_dpp v96, v96, v96 quad_perm:[1,0,3,2] row_mask:0xf bank_mask:0xf bound_ctrl:1
	v_pk_mul_f32 v[104:105], v[60:61], v[90:91]
	v_pk_mul_f32 v[124:125], v[56:57], v[90:91]
	v_add_f32_dpp v118, v0, v0 row_half_mirror row_mask:0xf bank_mask:0xf bound_ctrl:1
	v_add_f32_dpp v0, v96, v96 quad_perm:[2,3,0,1] row_mask:0xf bank_mask:0xf bound_ctrl:1
	v_mov_b32_e32 v96, v106
	v_mov_b32_e32 v97, v102
	v_mov_b32_e32 v102, v107
	v_pk_add_f32 v[96:97], v[96:97], v[102:103]
	v_mov_b32_e32 v98, v124
	v_mov_b32_e32 v99, v104
	s_waitcnt vmcnt(11)
	v_pk_mul_f32 v[126:127], v[50:51], v[88:89]
	s_waitcnt vmcnt(10)
	v_pk_mul_f32 v[100:101], v[46:47], v[88:89]
	s_waitcnt vmcnt(9)
	v_pk_mul_f32 v[132:133], v[42:43], v[88:89]
	s_waitcnt vmcnt(8)
	v_pk_mul_f32 v[136:137], v[38:39], v[88:89]
	v_pk_add_f32 v[96:97], v[98:99], v[96:97]
	v_mov_b32_e32 v104, v125
	v_pk_mul_f32 v[128:129], v[52:53], v[90:91]
	v_pk_mul_f32 v[130:131], v[48:49], v[90:91]
	v_pk_mul_f32 v[134:135], v[44:45], v[90:91]
	v_pk_mul_f32 v[138:139], v[40:41], v[90:91]
	v_pk_add_f32 v[96:97], v[104:105], v[96:97]
	v_mov_b32_e32 v102, v100
	v_mov_b32_e32 v103, v126
	v_mov_b32_e32 v126, v101
	v_mov_b32_e32 v104, v136
	v_mov_b32_e32 v105, v132
	v_mov_b32_e32 v132, v137
	v_pk_add_f32 v[100:101], v[102:103], v[126:127]
	v_mov_b32_e32 v102, v130
	v_mov_b32_e32 v103, v128
	v_pk_add_f32 v[104:105], v[104:105], v[132:133]
	v_mov_b32_e32 v106, v138
	v_mov_b32_e32 v107, v134
	v_pk_add_f32 v[100:101], v[102:103], v[100:101]
	v_mov_b32_e32 v128, v131
	v_pk_add_f32 v[104:105], v[106:107], v[104:105]
	v_mov_b32_e32 v134, v139
	v_pk_add_f32 v[100:101], v[128:129], v[100:101]
	v_pk_add_f32 v[104:105], v[134:135], v[104:105]
	v_mov_b32_dpp v99, v97 quad_perm:[1,0,3,2] row_mask:0xf bank_mask:0xf bound_ctrl:1
	v_mov_b32_dpp v98, v96 quad_perm:[1,0,3,2] row_mask:0xf bank_mask:0xf bound_ctrl:1
	v_mov_b32_dpp v103, v101 quad_perm:[1,0,3,2] row_mask:0xf bank_mask:0xf bound_ctrl:1
	v_mov_b32_dpp v102, v100 quad_perm:[1,0,3,2] row_mask:0xf bank_mask:0xf bound_ctrl:1
	v_mov_b32_dpp v107, v105 quad_perm:[1,0,3,2] row_mask:0xf bank_mask:0xf bound_ctrl:1
	v_mov_b32_dpp v106, v104 quad_perm:[1,0,3,2] row_mask:0xf bank_mask:0xf bound_ctrl:1
	v_pk_add_f32 v[96:97], v[96:97], v[98:99]
	v_pk_add_f32 v[100:101], v[100:101], v[102:103]
	v_pk_add_f32 v[104:105], v[104:105], v[106:107]
	v_mov_b32_dpp v99, v97 quad_perm:[2,3,0,1] row_mask:0xf bank_mask:0xf bound_ctrl:1
	v_mov_b32_dpp v98, v96 quad_perm:[2,3,0,1] row_mask:0xf bank_mask:0xf bound_ctrl:1
	v_mov_b32_dpp v103, v101 quad_perm:[2,3,0,1] row_mask:0xf bank_mask:0xf bound_ctrl:1
	v_mov_b32_dpp v102, v100 quad_perm:[2,3,0,1] row_mask:0xf bank_mask:0xf bound_ctrl:1
	v_mov_b32_dpp v107, v105 quad_perm:[2,3,0,1] row_mask:0xf bank_mask:0xf bound_ctrl:1
	v_mov_b32_dpp v106, v104 quad_perm:[2,3,0,1] row_mask:0xf bank_mask:0xf bound_ctrl:1
	v_pk_add_f32 v[96:97], v[96:97], v[98:99]
	v_pk_add_f32 v[100:101], v[100:101], v[102:103]
	v_pk_add_f32 v[104:105], v[104:105], v[106:107]
	v_mov_b32_dpp v99, v97 row_half_mirror row_mask:0xf bank_mask:0xf bound_ctrl:1
	v_mov_b32_dpp v98, v96 row_half_mirror row_mask:0xf bank_mask:0xf bound_ctrl:1
	v_mov_b32_dpp v103, v101 row_half_mirror row_mask:0xf bank_mask:0xf bound_ctrl:1
	v_mov_b32_dpp v102, v100 row_half_mirror row_mask:0xf bank_mask:0xf bound_ctrl:1
	v_mov_b32_dpp v107, v105 row_half_mirror row_mask:0xf bank_mask:0xf bound_ctrl:1
	v_mov_b32_dpp v106, v104 row_half_mirror row_mask:0xf bank_mask:0xf bound_ctrl:1
	v_add_f32_dpp v120, v0, v0 row_half_mirror row_mask:0xf bank_mask:0xf bound_ctrl:1
	v_pk_add_f32 v[96:97], v[96:97], v[98:99]
	v_pk_add_f32 v[100:101], v[100:101], v[102:103]
	v_pk_add_f32 v[104:105], v[104:105], v[106:107]
	v_mov_b32_dpp v119, v118 row_mirror row_mask:0xf bank_mask:0xf bound_ctrl:1
	v_mov_b32_dpp v121, v120 row_mirror row_mask:0xf bank_mask:0xf bound_ctrl:1
	v_mov_b32_dpp v99, v97 row_mirror row_mask:0xf bank_mask:0xf bound_ctrl:1
	v_mov_b32_dpp v98, v96 row_mirror row_mask:0xf bank_mask:0xf bound_ctrl:1
	v_mov_b32_dpp v103, v101 row_mirror row_mask:0xf bank_mask:0xf bound_ctrl:1
	v_mov_b32_dpp v102, v100 row_mirror row_mask:0xf bank_mask:0xf bound_ctrl:1
	v_mov_b32_dpp v107, v105 row_mirror row_mask:0xf bank_mask:0xf bound_ctrl:1
	v_mov_b32_dpp v106, v104 row_mirror row_mask:0xf bank_mask:0xf bound_ctrl:1
	s_and_saveexec_b64 s[28:29], s[54:55]
	s_cbranch_execz .LBB0_379
	s_waitcnt vmcnt(0)
	v_add_u32_e32 v0, 7, v112
	v_lshl_add_u32 v0, v0, v111, v85
	v_cmp_lt_i32_e32 vcc, 7, v0
	s_and_saveexec_b64 s[30:31], vcc
	s_cbranch_execz .LBB0_383
	v_add_u32_e32 v0, -8, v0
	v_lshlrev_b64 v[124:125], 11, v[0:1]
	v_lshl_add_u64 v[124:125], v[94:95], 0, v[124:125]
	global_store_dwordx4 v[124:125], v[66:69], off nt
	s_nop 0
	global_store_dwordx4 v[124:125], v[34:37], off offset:1024 nt
